# DV2 finishing loop: 16 rows per trip, all loads issued up front with counted vmcnt
# speedup vs baseline: 1.0058x; 1.0058x over previous
; __device__ __forceinline__ void phase_attn(const Params& p, int l, unsigned char* smem) {
;     ...
;             const float g0 = p.subln_g[lane * 2], g1 = p.subln_g[lane * 2 + 1];
; #pragma unroll 8
;             for (int i = 0; i < 32; ++i) {
;                 const int qrow = w * 32 + i;
;                 const float2 a0 = *(const float2*)(blk + (size_t)qrow * 128 + lane * 2);
;                 const float2 a1 = *(const float2*)(blk + (size_t)(256 + qrow) * 128 + lane * 2);
;                 const unsigned zz = *(const unsigned*)(p.sz + (grow0 + qrow) * D + hh * 128 + lane * 2);
;                 const float o0 = a0.x - lam * a1.x, o1 = a0.y - lam * a1.y;
;                 float ss = o0 * o0 + o1 * o1;
;                 ss = wave_sum64(ss);
;                 const float rstd = rsqrtf(ss * (1.0f / 128.0f) + EPS) * post;
;                 const float z0 = __uint_as_float(zz << 16), z1 = __uint_as_float(zz & 0xffff0000u);
;                 *(unsigned*)(p.og + (grow0 + qrow) * D + hh * 128 + lane * 2) = pk_bf16(o0 * rstd * g0 * z0, o1 * rstd * g1 * z1);
;             }
.LBB0_330:
	s_waitcnt vmcnt(63) expcnt(7) lgkmcnt(15)
	s_barrier
	global_load_dwordx2 v[2:3], v[214:215], off
	v_readlane_b32 s6, v254, 43
	s_or_b32 s6, s37, s6
	s_and_b64 s[4:5], s[4:5], exec
	v_readlane_b32 s4, v254, 42
	s_cselect_b32 s4, s6, s4
	s_mov_b32 s5, s83
	v_lshl_add_u64 v[4:5], v[212:213], 0, s[4:5]
	v_lshlrev_b64 v[6:7], 11, v[4:5]
	s_lshl_b32 s82, s36, 8
	v_lshl_add_u64 v[4:5], v[216:217], 0, v[6:7]
	v_lshl_add_u64 v[6:7], v[218:219], 0, v[6:7]
	s_mov_b64 s[4:5], 0
	s_movk_i32 s6, 0x2000
	s_mov_b32 s7, 0x800000
	s_movk_i32 s8, 0x1000
	s_movk_i32 s9, 0x3000
	s_mov_b64 s[10:11], 0x1000
	s_mov_b64 s[12:13], 0x8000
.Ldv2fin_loop:
	v_lshl_add_u64 v[8:9], v[220:221], 0, s[4:5]
	v_lshl_add_u64 v[10:11], v[222:223], 0, s[4:5]
	v_lshl_add_u64 v[112:113], v[6:7], 0, s[82:83]
	v_lshl_add_u64 v[128:129], v[4:5], 0, s[82:83]
	v_lshl_add_u64 v[18:19], v[8:9], 0, s[10:11]
	v_lshl_add_u64 v[20:21], v[10:11], 0, s[10:11]
	v_lshl_add_u64 v[114:115], v[112:113], 0, s[10:11]
	v_lshl_add_u64 v[116:117], v[114:115], 0, s[10:11]
	v_lshl_add_u64 v[118:119], v[116:117], 0, s[10:11]
	v_lshl_add_u64 v[120:121], v[118:119], 0, s[10:11]
	v_lshl_add_u64 v[122:123], v[120:121], 0, s[10:11]
	v_lshl_add_u64 v[124:125], v[122:123], 0, s[10:11]
	v_lshl_add_u64 v[126:127], v[124:125], 0, s[10:11]
	v_lshl_add_u64 v[130:131], v[128:129], 0, s[10:11]
	v_lshl_add_u64 v[132:133], v[130:131], 0, s[10:11]
	v_lshl_add_u64 v[134:135], v[132:133], 0, s[10:11]
	v_lshl_add_u64 v[136:137], v[134:135], 0, s[10:11]
	v_lshl_add_u64 v[138:139], v[136:137], 0, s[10:11]
	v_lshl_add_u64 v[140:141], v[138:139], 0, s[10:11]
	v_lshl_add_u64 v[142:143], v[140:141], 0, s[10:11]
	global_load_dwordx2 v[30:31], v[8:9], off
	global_load_dwordx2 v[32:33], v[10:11], off
	global_load_dword v94, v[112:113], off
	global_load_dwordx2 v[34:35], v[8:9], off offset:512
	global_load_dwordx2 v[36:37], v[10:11], off offset:512
	global_load_dword v95, v[112:113], off offset:2048
	global_load_dwordx2 v[38:39], v[8:9], off offset:1024
	global_load_dwordx2 v[40:41], v[10:11], off offset:1024
	global_load_dword v96, v[114:115], off
	global_load_dwordx2 v[42:43], v[8:9], off offset:1536
	global_load_dwordx2 v[44:45], v[10:11], off offset:1536
	global_load_dword v97, v[114:115], off offset:2048
	global_load_dwordx2 v[46:47], v[8:9], off offset:2048
	global_load_dwordx2 v[48:49], v[10:11], off offset:2048
	global_load_dword v98, v[116:117], off
	global_load_dwordx2 v[50:51], v[8:9], off offset:2560
	global_load_dwordx2 v[52:53], v[10:11], off offset:2560
	global_load_dword v99, v[116:117], off offset:2048
	global_load_dwordx2 v[54:55], v[8:9], off offset:3072
	global_load_dwordx2 v[56:57], v[10:11], off offset:3072
	global_load_dword v100, v[118:119], off
	global_load_dwordx2 v[58:59], v[8:9], off offset:3584
	global_load_dwordx2 v[60:61], v[10:11], off offset:3584
	global_load_dword v101, v[118:119], off offset:2048
	global_load_dwordx2 v[62:63], v[18:19], off
	global_load_dwordx2 v[64:65], v[20:21], off
	global_load_dword v102, v[120:121], off
	global_load_dwordx2 v[66:67], v[18:19], off offset:512
	global_load_dwordx2 v[68:69], v[20:21], off offset:512
	global_load_dword v103, v[120:121], off offset:2048
	global_load_dwordx2 v[70:71], v[18:19], off offset:1024
	global_load_dwordx2 v[72:73], v[20:21], off offset:1024
	global_load_dword v104, v[122:123], off
	global_load_dwordx2 v[74:75], v[18:19], off offset:1536
	global_load_dwordx2 v[76:77], v[20:21], off offset:1536
	global_load_dword v105, v[122:123], off offset:2048
	global_load_dwordx2 v[78:79], v[18:19], off offset:2048
	global_load_dwordx2 v[80:81], v[20:21], off offset:2048
	global_load_dword v106, v[124:125], off
	global_load_dwordx2 v[82:83], v[18:19], off offset:2560
	global_load_dwordx2 v[84:85], v[20:21], off offset:2560
	global_load_dword v107, v[124:125], off offset:2048
	global_load_dwordx2 v[86:87], v[18:19], off offset:3072
	global_load_dwordx2 v[88:89], v[20:21], off offset:3072
	global_load_dword v108, v[126:127], off
	global_load_dwordx2 v[90:91], v[18:19], off offset:3584
	global_load_dwordx2 v[92:93], v[20:21], off offset:3584
	global_load_dword v109, v[126:127], off offset:2048
	s_add_u32 s4, s4, 0x2000
	s_addc_u32 s5, s5, 0
	v_lshl_add_u64 v[4:5], v[4:5], 0, s[12:13]
	v_lshl_add_u64 v[6:7], v[6:7], 0, s[12:13]
	s_waitcnt vmcnt(45)
	v_fma_f32 v31, -v17, v33, v31
	v_fma_f32 v30, -v17, v32, v30
	v_mul_f32_e32 v33, v31, v31
	v_fmac_f32_e32 v33, v30, v30
	v_lshlrev_b32_e32 v32, 16, v94
	v_and_b32_e32 v94, 0xffff0000, v94
	v_add_f32_dpp v33, v33, v33 quad_perm:[1,0,3,2] row_mask:0xf bank_mask:0xf bound_ctrl:1
	s_nop 1
	v_add_f32_dpp v33, v33, v33 quad_perm:[2,3,0,1] row_mask:0xf bank_mask:0xf bound_ctrl:1
	s_nop 1
	v_add_f32_dpp v33, v33, v33 row_half_mirror row_mask:0xf bank_mask:0xf bound_ctrl:1
	s_nop 1
	v_add_f32_dpp v33, v33, v33 row_mirror row_mask:0xf bank_mask:0xf bound_ctrl:1
	v_mov_b32_e32 v110, v33
	s_nop 1
	v_permlane16_swap_b32_e32 v33, v110
	v_add_f32_e32 v33, v33, v110
	v_mov_b32_e32 v110, v33
	s_nop 1
	v_permlane32_swap_b32_e32 v33, v110
	v_add_f32_e32 v33, v33, v110
	v_fmamk_f32 v33, v33, 0x3c000000, v236
	v_mul_f32_e32 v110, 0x4b800000, v33
	v_cmp_gt_f32_e32 vcc, s7, v33
	s_nop 1
	v_cndmask_b32_e32 v33, v33, v110, vcc
	v_rsq_f32_e32 v33, v33
	s_nop 0
	v_mul_f32_e32 v110, 0x45800000, v33
	v_cndmask_b32_e32 v33, v33, v110, vcc
	v_mul_f32_e32 v33, v235, v33
	v_mul_f32_e32 v31, v31, v33
	v_mul_f32_e32 v30, v30, v33
	v_mul_f32_e32 v31, v3, v31
	v_mul_f32_e32 v30, v2, v30
	v_mul_f32_e32 v94, v31, v94
	v_mul_f32_e32 v30, v30, v32
	v_cvt_pk_bf16_f32 v94, v30, v94
	global_store_dword v[128:129], v94, off
	s_waitcnt vmcnt(43)
; __device__ __forceinline__ void phase_attn(const Params& p, int l, unsigned char* smem) {
;     ...
;             for (int i = 0; i < 32; ++i) {
;                 const int qrow = w * 32 + i;
;                 const float2 a0 = *(const float2*)(blk + (size_t)qrow * 128 + lane * 2);
;                 const float2 a1 = *(const float2*)(blk + (size_t)(256 + qrow) * 128 + lane * 2);
;                 const unsigned zz = *(const unsigned*)(p.sz + (grow0 + qrow) * D + hh * 128 + lane * 2);
;                 const float o0 = a0.x - lam * a1.x, o1 = a0.y - lam * a1.y;
;                 float ss = o0 * o0 + o1 * o1;
;                 ss = wave_sum64(ss);
;                 const float rstd = rsqrtf(ss * (1.0f / 128.0f) + EPS) * post;
;                 const float z0 = __uint_as_float(zz << 16), z1 = __uint_as_float(zz & 0xffff0000u);
;                 *(unsigned*)(p.og + (grow0 + qrow) * D + hh * 128 + lane * 2) = pk_bf16(o0 * rstd * g0 * z0, o1 * rstd * g1 * z1);
;             }
	v_fma_f32 v35, -v17, v37, v35
	v_fma_f32 v34, -v17, v36, v34
	v_mul_f32_e32 v37, v35, v35
	v_fmac_f32_e32 v37, v34, v34
	v_lshlrev_b32_e32 v36, 16, v95
	v_and_b32_e32 v95, 0xffff0000, v95
	v_add_f32_dpp v37, v37, v37 quad_perm:[1,0,3,2] row_mask:0xf bank_mask:0xf bound_ctrl:1
	s_nop 1
	v_add_f32_dpp v37, v37, v37 quad_perm:[2,3,0,1] row_mask:0xf bank_mask:0xf bound_ctrl:1
	s_nop 1
	v_add_f32_dpp v37, v37, v37 row_half_mirror row_mask:0xf bank_mask:0xf bound_ctrl:1
	s_nop 1
	v_add_f32_dpp v37, v37, v37 row_mirror row_mask:0xf bank_mask:0xf bound_ctrl:1
	v_mov_b32_e32 v110, v37
	s_nop 1
	v_permlane16_swap_b32_e32 v37, v110
	v_add_f32_e32 v37, v37, v110
	v_mov_b32_e32 v110, v37
	s_nop 1
	v_permlane32_swap_b32_e32 v37, v110
	v_add_f32_e32 v37, v37, v110
	v_fmamk_f32 v37, v37, 0x3c000000, v236
	v_mul_f32_e32 v110, 0x4b800000, v37
	v_cmp_gt_f32_e32 vcc, s7, v37
	s_nop 1
	v_cndmask_b32_e32 v37, v37, v110, vcc
	v_rsq_f32_e32 v37, v37
	s_nop 0
	v_mul_f32_e32 v110, 0x45800000, v37
	v_cndmask_b32_e32 v37, v37, v110, vcc
	v_mul_f32_e32 v37, v235, v37
	v_mul_f32_e32 v35, v35, v37
	v_mul_f32_e32 v34, v34, v37
	v_mul_f32_e32 v35, v3, v35
	v_mul_f32_e32 v34, v2, v34
	v_mul_f32_e32 v95, v35, v95
	v_mul_f32_e32 v34, v34, v36
	v_cvt_pk_bf16_f32 v95, v34, v95
	global_store_dword v[128:129], v95, off offset:2048
	s_waitcnt vmcnt(41)
	v_fma_f32 v39, -v17, v41, v39
	v_fma_f32 v38, -v17, v40, v38
	v_mul_f32_e32 v41, v39, v39
	v_fmac_f32_e32 v41, v38, v38
	v_lshlrev_b32_e32 v40, 16, v96
	v_and_b32_e32 v96, 0xffff0000, v96
	v_add_f32_dpp v41, v41, v41 quad_perm:[1,0,3,2] row_mask:0xf bank_mask:0xf bound_ctrl:1
	s_nop 1
	v_add_f32_dpp v41, v41, v41 quad_perm:[2,3,0,1] row_mask:0xf bank_mask:0xf bound_ctrl:1
	s_nop 1
	v_add_f32_dpp v41, v41, v41 row_half_mirror row_mask:0xf bank_mask:0xf bound_ctrl:1
	s_nop 1
	v_add_f32_dpp v41, v41, v41 row_mirror row_mask:0xf bank_mask:0xf bound_ctrl:1
	v_mov_b32_e32 v110, v41
	s_nop 1
	v_permlane16_swap_b32_e32 v41, v110
	v_add_f32_e32 v41, v41, v110
	v_mov_b32_e32 v110, v41
	s_nop 1
	v_permlane32_swap_b32_e32 v41, v110
	v_add_f32_e32 v41, v41, v110
	v_fmamk_f32 v41, v41, 0x3c000000, v236
	v_mul_f32_e32 v110, 0x4b800000, v41
	v_cmp_gt_f32_e32 vcc, s7, v41
	s_nop 1
	v_cndmask_b32_e32 v41, v41, v110, vcc
	v_rsq_f32_e32 v41, v41
	s_nop 0
	v_mul_f32_e32 v110, 0x45800000, v41
	v_cndmask_b32_e32 v41, v41, v110, vcc
	v_mul_f32_e32 v41, v235, v41
	v_mul_f32_e32 v39, v39, v41
	v_mul_f32_e32 v38, v38, v41
	v_mul_f32_e32 v39, v3, v39
	v_mul_f32_e32 v38, v2, v38
	v_mul_f32_e32 v96, v39, v96
	v_mul_f32_e32 v38, v38, v40
	v_cvt_pk_bf16_f32 v96, v38, v96
	global_store_dword v[130:131], v96, off
	s_waitcnt vmcnt(39)
	v_fma_f32 v43, -v17, v45, v43
	v_fma_f32 v42, -v17, v44, v42
	v_mul_f32_e32 v45, v43, v43
	v_fmac_f32_e32 v45, v42, v42
	v_lshlrev_b32_e32 v44, 16, v97
	v_and_b32_e32 v97, 0xffff0000, v97
	v_add_f32_dpp v45, v45, v45 quad_perm:[1,0,3,2] row_mask:0xf bank_mask:0xf bound_ctrl:1
	s_nop 1
	v_add_f32_dpp v45, v45, v45 quad_perm:[2,3,0,1] row_mask:0xf bank_mask:0xf bound_ctrl:1
	s_nop 1
	v_add_f32_dpp v45, v45, v45 row_half_mirror row_mask:0xf bank_mask:0xf bound_ctrl:1
	s_nop 1
	v_add_f32_dpp v45, v45, v45 row_mirror row_mask:0xf bank_mask:0xf bound_ctrl:1
	v_mov_b32_e32 v110, v45
	s_nop 1
	v_permlane16_swap_b32_e32 v45, v110
	v_add_f32_e32 v45, v45, v110
	v_mov_b32_e32 v110, v45
	s_nop 1
	v_permlane32_swap_b32_e32 v45, v110
	v_add_f32_e32 v45, v45, v110
	v_fmamk_f32 v45, v45, 0x3c000000, v236
	v_mul_f32_e32 v110, 0x4b800000, v45
	v_cmp_gt_f32_e32 vcc, s7, v45
	s_nop 1
	v_cndmask_b32_e32 v45, v45, v110, vcc
	v_rsq_f32_e32 v45, v45
	s_nop 0
	v_mul_f32_e32 v110, 0x45800000, v45
	v_cndmask_b32_e32 v45, v45, v110, vcc
	v_mul_f32_e32 v45, v235, v45
	v_mul_f32_e32 v43, v43, v45
	v_mul_f32_e32 v42, v42, v45
	v_mul_f32_e32 v43, v3, v43
	v_mul_f32_e32 v42, v2, v42
	v_mul_f32_e32 v97, v43, v97
	v_mul_f32_e32 v42, v42, v44
	v_cvt_pk_bf16_f32 v97, v42, v97
	global_store_dword v[130:131], v97, off offset:2048
	s_waitcnt vmcnt(37)
	v_fma_f32 v47, -v17, v49, v47
	v_fma_f32 v46, -v17, v48, v46
	v_mul_f32_e32 v49, v47, v47
	v_fmac_f32_e32 v49, v46, v46
	v_lshlrev_b32_e32 v48, 16, v98
	v_and_b32_e32 v98, 0xffff0000, v98
	v_add_f32_dpp v49, v49, v49 quad_perm:[1,0,3,2] row_mask:0xf bank_mask:0xf bound_ctrl:1
	s_nop 1
	v_add_f32_dpp v49, v49, v49 quad_perm:[2,3,0,1] row_mask:0xf bank_mask:0xf bound_ctrl:1
	s_nop 1
	v_add_f32_dpp v49, v49, v49 row_half_mirror row_mask:0xf bank_mask:0xf bound_ctrl:1
	s_nop 1
	v_add_f32_dpp v49, v49, v49 row_mirror row_mask:0xf bank_mask:0xf bound_ctrl:1
	v_mov_b32_e32 v110, v49
	s_nop 1
	v_permlane16_swap_b32_e32 v49, v110
	v_add_f32_e32 v49, v49, v110
	v_mov_b32_e32 v110, v49
	s_nop 1
	v_permlane32_swap_b32_e32 v49, v110
	v_add_f32_e32 v49, v49, v110
	v_fmamk_f32 v49, v49, 0x3c000000, v236
	v_mul_f32_e32 v110, 0x4b800000, v49
	v_cmp_gt_f32_e32 vcc, s7, v49
	s_nop 1
	v_cndmask_b32_e32 v49, v49, v110, vcc
	v_rsq_f32_e32 v49, v49
	s_nop 0
	v_mul_f32_e32 v110, 0x45800000, v49
	v_cndmask_b32_e32 v49, v49, v110, vcc
	v_mul_f32_e32 v49, v235, v49
	v_mul_f32_e32 v47, v47, v49
	v_mul_f32_e32 v46, v46, v49
	v_mul_f32_e32 v47, v3, v47
	v_mul_f32_e32 v46, v2, v46
	v_mul_f32_e32 v98, v47, v98
	v_mul_f32_e32 v46, v46, v48
	v_cvt_pk_bf16_f32 v98, v46, v98
	global_store_dword v[132:133], v98, off
	s_waitcnt vmcnt(35)
; __device__ __forceinline__ void phase_attn(const Params& p, int l, unsigned char* smem) {
;     ...
;             for (int i = 0; i < 32; ++i) {
;                 const int qrow = w * 32 + i;
;                 const float2 a0 = *(const float2*)(blk + (size_t)qrow * 128 + lane * 2);
;                 const float2 a1 = *(const float2*)(blk + (size_t)(256 + qrow) * 128 + lane * 2);
;                 const unsigned zz = *(const unsigned*)(p.sz + (grow0 + qrow) * D + hh * 128 + lane * 2);
;                 const float o0 = a0.x - lam * a1.x, o1 = a0.y - lam * a1.y;
;                 float ss = o0 * o0 + o1 * o1;
;                 ss = wave_sum64(ss);
;                 const float rstd = rsqrtf(ss * (1.0f / 128.0f) + EPS) * post;
;                 const float z0 = __uint_as_float(zz << 16), z1 = __uint_as_float(zz & 0xffff0000u);
;                 *(unsigned*)(p.og + (grow0 + qrow) * D + hh * 128 + lane * 2) = pk_bf16(o0 * rstd * g0 * z0, o1 * rstd * g1 * z1);
;             }
	v_fma_f32 v51, -v17, v53, v51
	v_fma_f32 v50, -v17, v52, v50
	v_mul_f32_e32 v53, v51, v51
	v_fmac_f32_e32 v53, v50, v50
	v_lshlrev_b32_e32 v52, 16, v99
	v_and_b32_e32 v99, 0xffff0000, v99
	v_add_f32_dpp v53, v53, v53 quad_perm:[1,0,3,2] row_mask:0xf bank_mask:0xf bound_ctrl:1
	s_nop 1
	v_add_f32_dpp v53, v53, v53 quad_perm:[2,3,0,1] row_mask:0xf bank_mask:0xf bound_ctrl:1
	s_nop 1
	v_add_f32_dpp v53, v53, v53 row_half_mirror row_mask:0xf bank_mask:0xf bound_ctrl:1
	s_nop 1
	v_add_f32_dpp v53, v53, v53 row_mirror row_mask:0xf bank_mask:0xf bound_ctrl:1
	v_mov_b32_e32 v110, v53
	s_nop 1
	v_permlane16_swap_b32_e32 v53, v110
	v_add_f32_e32 v53, v53, v110
	v_mov_b32_e32 v110, v53
	s_nop 1
	v_permlane32_swap_b32_e32 v53, v110
	v_add_f32_e32 v53, v53, v110
	v_fmamk_f32 v53, v53, 0x3c000000, v236
	v_mul_f32_e32 v110, 0x4b800000, v53
	v_cmp_gt_f32_e32 vcc, s7, v53
	s_nop 1
	v_cndmask_b32_e32 v53, v53, v110, vcc
	v_rsq_f32_e32 v53, v53
	s_nop 0
	v_mul_f32_e32 v110, 0x45800000, v53
	v_cndmask_b32_e32 v53, v53, v110, vcc
	v_mul_f32_e32 v53, v235, v53
	v_mul_f32_e32 v51, v51, v53
	v_mul_f32_e32 v50, v50, v53
	v_mul_f32_e32 v51, v3, v51
	v_mul_f32_e32 v50, v2, v50
	v_mul_f32_e32 v99, v51, v99
	v_mul_f32_e32 v50, v50, v52
	v_cvt_pk_bf16_f32 v99, v50, v99
	global_store_dword v[132:133], v99, off offset:2048
	s_waitcnt vmcnt(33)
	v_fma_f32 v55, -v17, v57, v55
	v_fma_f32 v54, -v17, v56, v54
	v_mul_f32_e32 v57, v55, v55
	v_fmac_f32_e32 v57, v54, v54
	v_lshlrev_b32_e32 v56, 16, v100
	v_and_b32_e32 v100, 0xffff0000, v100
	v_add_f32_dpp v57, v57, v57 quad_perm:[1,0,3,2] row_mask:0xf bank_mask:0xf bound_ctrl:1
	s_nop 1
	v_add_f32_dpp v57, v57, v57 quad_perm:[2,3,0,1] row_mask:0xf bank_mask:0xf bound_ctrl:1
	s_nop 1
	v_add_f32_dpp v57, v57, v57 row_half_mirror row_mask:0xf bank_mask:0xf bound_ctrl:1
	s_nop 1
	v_add_f32_dpp v57, v57, v57 row_mirror row_mask:0xf bank_mask:0xf bound_ctrl:1
	v_mov_b32_e32 v110, v57
	s_nop 1
	v_permlane16_swap_b32_e32 v57, v110
	v_add_f32_e32 v57, v57, v110
	v_mov_b32_e32 v110, v57
	s_nop 1
	v_permlane32_swap_b32_e32 v57, v110
	v_add_f32_e32 v57, v57, v110
	v_fmamk_f32 v57, v57, 0x3c000000, v236
	v_mul_f32_e32 v110, 0x4b800000, v57
	v_cmp_gt_f32_e32 vcc, s7, v57
	s_nop 1
	v_cndmask_b32_e32 v57, v57, v110, vcc
	v_rsq_f32_e32 v57, v57
	s_nop 0
	v_mul_f32_e32 v110, 0x45800000, v57
	v_cndmask_b32_e32 v57, v57, v110, vcc
	v_mul_f32_e32 v57, v235, v57
	v_mul_f32_e32 v55, v55, v57
	v_mul_f32_e32 v54, v54, v57
	v_mul_f32_e32 v55, v3, v55
	v_mul_f32_e32 v54, v2, v54
	v_mul_f32_e32 v100, v55, v100
	v_mul_f32_e32 v54, v54, v56
	v_cvt_pk_bf16_f32 v100, v54, v100
	global_store_dword v[134:135], v100, off
	s_waitcnt vmcnt(31)
	v_fma_f32 v59, -v17, v61, v59
	v_fma_f32 v58, -v17, v60, v58
	v_mul_f32_e32 v61, v59, v59
	v_fmac_f32_e32 v61, v58, v58
	v_lshlrev_b32_e32 v60, 16, v101
	v_and_b32_e32 v101, 0xffff0000, v101
	v_add_f32_dpp v61, v61, v61 quad_perm:[1,0,3,2] row_mask:0xf bank_mask:0xf bound_ctrl:1
	s_nop 1
	v_add_f32_dpp v61, v61, v61 quad_perm:[2,3,0,1] row_mask:0xf bank_mask:0xf bound_ctrl:1
	s_nop 1
	v_add_f32_dpp v61, v61, v61 row_half_mirror row_mask:0xf bank_mask:0xf bound_ctrl:1
	s_nop 1
	v_add_f32_dpp v61, v61, v61 row_mirror row_mask:0xf bank_mask:0xf bound_ctrl:1
	v_mov_b32_e32 v110, v61
	s_nop 1
	v_permlane16_swap_b32_e32 v61, v110
	v_add_f32_e32 v61, v61, v110
	v_mov_b32_e32 v110, v61
	s_nop 1
	v_permlane32_swap_b32_e32 v61, v110
	v_add_f32_e32 v61, v61, v110
	v_fmamk_f32 v61, v61, 0x3c000000, v236
	v_mul_f32_e32 v110, 0x4b800000, v61
	v_cmp_gt_f32_e32 vcc, s7, v61
	s_nop 1
	v_cndmask_b32_e32 v61, v61, v110, vcc
	v_rsq_f32_e32 v61, v61
	s_nop 0
	v_mul_f32_e32 v110, 0x45800000, v61
	v_cndmask_b32_e32 v61, v61, v110, vcc
	v_mul_f32_e32 v61, v235, v61
	v_mul_f32_e32 v59, v59, v61
	v_mul_f32_e32 v58, v58, v61
	v_mul_f32_e32 v59, v3, v59
	v_mul_f32_e32 v58, v2, v58
	v_mul_f32_e32 v101, v59, v101
	v_mul_f32_e32 v58, v58, v60
	v_cvt_pk_bf16_f32 v101, v58, v101
	global_store_dword v[134:135], v101, off offset:2048
	s_waitcnt vmcnt(29)
	v_fma_f32 v63, -v17, v65, v63
	v_fma_f32 v62, -v17, v64, v62
	v_mul_f32_e32 v65, v63, v63
	v_fmac_f32_e32 v65, v62, v62
	v_lshlrev_b32_e32 v64, 16, v102
	v_and_b32_e32 v102, 0xffff0000, v102
	v_add_f32_dpp v65, v65, v65 quad_perm:[1,0,3,2] row_mask:0xf bank_mask:0xf bound_ctrl:1
	s_nop 1
	v_add_f32_dpp v65, v65, v65 quad_perm:[2,3,0,1] row_mask:0xf bank_mask:0xf bound_ctrl:1
	s_nop 1
	v_add_f32_dpp v65, v65, v65 row_half_mirror row_mask:0xf bank_mask:0xf bound_ctrl:1
	s_nop 1
	v_add_f32_dpp v65, v65, v65 row_mirror row_mask:0xf bank_mask:0xf bound_ctrl:1
	v_mov_b32_e32 v110, v65
	s_nop 1
	v_permlane16_swap_b32_e32 v65, v110
	v_add_f32_e32 v65, v65, v110
	v_mov_b32_e32 v110, v65
	s_nop 1
	v_permlane32_swap_b32_e32 v65, v110
	v_add_f32_e32 v65, v65, v110
	v_fmamk_f32 v65, v65, 0x3c000000, v236
	v_mul_f32_e32 v110, 0x4b800000, v65
	v_cmp_gt_f32_e32 vcc, s7, v65
	s_nop 1
	v_cndmask_b32_e32 v65, v65, v110, vcc
	v_rsq_f32_e32 v65, v65
	s_nop 0
	v_mul_f32_e32 v110, 0x45800000, v65
	v_cndmask_b32_e32 v65, v65, v110, vcc
	v_mul_f32_e32 v65, v235, v65
	v_mul_f32_e32 v63, v63, v65
	v_mul_f32_e32 v62, v62, v65
	v_mul_f32_e32 v63, v3, v63
	v_mul_f32_e32 v62, v2, v62
	v_mul_f32_e32 v102, v63, v102
	v_mul_f32_e32 v62, v62, v64
	v_cvt_pk_bf16_f32 v102, v62, v102
	global_store_dword v[136:137], v102, off
	s_waitcnt vmcnt(27)
; __device__ __forceinline__ void phase_attn(const Params& p, int l, unsigned char* smem) {
;     ...
;             for (int i = 0; i < 32; ++i) {
;                 const int qrow = w * 32 + i;
;                 const float2 a0 = *(const float2*)(blk + (size_t)qrow * 128 + lane * 2);
;                 const float2 a1 = *(const float2*)(blk + (size_t)(256 + qrow) * 128 + lane * 2);
;                 const unsigned zz = *(const unsigned*)(p.sz + (grow0 + qrow) * D + hh * 128 + lane * 2);
;                 const float o0 = a0.x - lam * a1.x, o1 = a0.y - lam * a1.y;
;                 float ss = o0 * o0 + o1 * o1;
;                 ss = wave_sum64(ss);
;                 const float rstd = rsqrtf(ss * (1.0f / 128.0f) + EPS) * post;
;                 const float z0 = __uint_as_float(zz << 16), z1 = __uint_as_float(zz & 0xffff0000u);
;                 *(unsigned*)(p.og + (grow0 + qrow) * D + hh * 128 + lane * 2) = pk_bf16(o0 * rstd * g0 * z0, o1 * rstd * g1 * z1);
;             }
	v_fma_f32 v67, -v17, v69, v67
	v_fma_f32 v66, -v17, v68, v66
	v_mul_f32_e32 v69, v67, v67
	v_fmac_f32_e32 v69, v66, v66
	v_lshlrev_b32_e32 v68, 16, v103
	v_and_b32_e32 v103, 0xffff0000, v103
	v_add_f32_dpp v69, v69, v69 quad_perm:[1,0,3,2] row_mask:0xf bank_mask:0xf bound_ctrl:1
	s_nop 1
	v_add_f32_dpp v69, v69, v69 quad_perm:[2,3,0,1] row_mask:0xf bank_mask:0xf bound_ctrl:1
	s_nop 1
	v_add_f32_dpp v69, v69, v69 row_half_mirror row_mask:0xf bank_mask:0xf bound_ctrl:1
	s_nop 1
	v_add_f32_dpp v69, v69, v69 row_mirror row_mask:0xf bank_mask:0xf bound_ctrl:1
	v_mov_b32_e32 v110, v69
	s_nop 1
	v_permlane16_swap_b32_e32 v69, v110
	v_add_f32_e32 v69, v69, v110
	v_mov_b32_e32 v110, v69
	s_nop 1
	v_permlane32_swap_b32_e32 v69, v110
	v_add_f32_e32 v69, v69, v110
	v_fmamk_f32 v69, v69, 0x3c000000, v236
	v_mul_f32_e32 v110, 0x4b800000, v69
	v_cmp_gt_f32_e32 vcc, s7, v69
	s_nop 1
	v_cndmask_b32_e32 v69, v69, v110, vcc
	v_rsq_f32_e32 v69, v69
	s_nop 0
	v_mul_f32_e32 v110, 0x45800000, v69
	v_cndmask_b32_e32 v69, v69, v110, vcc
	v_mul_f32_e32 v69, v235, v69
	v_mul_f32_e32 v67, v67, v69
	v_mul_f32_e32 v66, v66, v69
	v_mul_f32_e32 v67, v3, v67
	v_mul_f32_e32 v66, v2, v66
	v_mul_f32_e32 v103, v67, v103
	v_mul_f32_e32 v66, v66, v68
	v_cvt_pk_bf16_f32 v103, v66, v103
	global_store_dword v[136:137], v103, off offset:2048
	s_waitcnt vmcnt(25)
	v_fma_f32 v71, -v17, v73, v71
	v_fma_f32 v70, -v17, v72, v70
	v_mul_f32_e32 v73, v71, v71
	v_fmac_f32_e32 v73, v70, v70
	v_lshlrev_b32_e32 v72, 16, v104
	v_and_b32_e32 v104, 0xffff0000, v104
	v_add_f32_dpp v73, v73, v73 quad_perm:[1,0,3,2] row_mask:0xf bank_mask:0xf bound_ctrl:1
	s_nop 1
	v_add_f32_dpp v73, v73, v73 quad_perm:[2,3,0,1] row_mask:0xf bank_mask:0xf bound_ctrl:1
	s_nop 1
	v_add_f32_dpp v73, v73, v73 row_half_mirror row_mask:0xf bank_mask:0xf bound_ctrl:1
	s_nop 1
	v_add_f32_dpp v73, v73, v73 row_mirror row_mask:0xf bank_mask:0xf bound_ctrl:1
	v_mov_b32_e32 v110, v73
	s_nop 1
	v_permlane16_swap_b32_e32 v73, v110
	v_add_f32_e32 v73, v73, v110
	v_mov_b32_e32 v110, v73
	s_nop 1
	v_permlane32_swap_b32_e32 v73, v110
	v_add_f32_e32 v73, v73, v110
	v_fmamk_f32 v73, v73, 0x3c000000, v236
	v_mul_f32_e32 v110, 0x4b800000, v73
	v_cmp_gt_f32_e32 vcc, s7, v73
	s_nop 1
	v_cndmask_b32_e32 v73, v73, v110, vcc
	v_rsq_f32_e32 v73, v73
	s_nop 0
	v_mul_f32_e32 v110, 0x45800000, v73
	v_cndmask_b32_e32 v73, v73, v110, vcc
	v_mul_f32_e32 v73, v235, v73
	v_mul_f32_e32 v71, v71, v73
	v_mul_f32_e32 v70, v70, v73
	v_mul_f32_e32 v71, v3, v71
	v_mul_f32_e32 v70, v2, v70
	v_mul_f32_e32 v104, v71, v104
	v_mul_f32_e32 v70, v70, v72
	v_cvt_pk_bf16_f32 v104, v70, v104
	global_store_dword v[138:139], v104, off
	s_waitcnt vmcnt(23)
	v_fma_f32 v75, -v17, v77, v75
	v_fma_f32 v74, -v17, v76, v74
	v_mul_f32_e32 v77, v75, v75
	v_fmac_f32_e32 v77, v74, v74
	v_lshlrev_b32_e32 v76, 16, v105
	v_and_b32_e32 v105, 0xffff0000, v105
	v_add_f32_dpp v77, v77, v77 quad_perm:[1,0,3,2] row_mask:0xf bank_mask:0xf bound_ctrl:1
	s_nop 1
	v_add_f32_dpp v77, v77, v77 quad_perm:[2,3,0,1] row_mask:0xf bank_mask:0xf bound_ctrl:1
	s_nop 1
	v_add_f32_dpp v77, v77, v77 row_half_mirror row_mask:0xf bank_mask:0xf bound_ctrl:1
	s_nop 1
	v_add_f32_dpp v77, v77, v77 row_mirror row_mask:0xf bank_mask:0xf bound_ctrl:1
	v_mov_b32_e32 v110, v77
	s_nop 1
	v_permlane16_swap_b32_e32 v77, v110
	v_add_f32_e32 v77, v77, v110
	v_mov_b32_e32 v110, v77
	s_nop 1
	v_permlane32_swap_b32_e32 v77, v110
	v_add_f32_e32 v77, v77, v110
	v_fmamk_f32 v77, v77, 0x3c000000, v236
	v_mul_f32_e32 v110, 0x4b800000, v77
	v_cmp_gt_f32_e32 vcc, s7, v77
	s_nop 1
	v_cndmask_b32_e32 v77, v77, v110, vcc
	v_rsq_f32_e32 v77, v77
	s_nop 0
	v_mul_f32_e32 v110, 0x45800000, v77
	v_cndmask_b32_e32 v77, v77, v110, vcc
	v_mul_f32_e32 v77, v235, v77
	v_mul_f32_e32 v75, v75, v77
	v_mul_f32_e32 v74, v74, v77
	v_mul_f32_e32 v75, v3, v75
	v_mul_f32_e32 v74, v2, v74
	v_mul_f32_e32 v105, v75, v105
	v_mul_f32_e32 v74, v74, v76
	v_cvt_pk_bf16_f32 v105, v74, v105
	global_store_dword v[138:139], v105, off offset:2048
	s_waitcnt vmcnt(21)
	v_fma_f32 v79, -v17, v81, v79
	v_fma_f32 v78, -v17, v80, v78
	v_mul_f32_e32 v81, v79, v79
	v_fmac_f32_e32 v81, v78, v78
	v_lshlrev_b32_e32 v80, 16, v106
	v_and_b32_e32 v106, 0xffff0000, v106
	v_add_f32_dpp v81, v81, v81 quad_perm:[1,0,3,2] row_mask:0xf bank_mask:0xf bound_ctrl:1
	s_nop 1
	v_add_f32_dpp v81, v81, v81 quad_perm:[2,3,0,1] row_mask:0xf bank_mask:0xf bound_ctrl:1
	s_nop 1
	v_add_f32_dpp v81, v81, v81 row_half_mirror row_mask:0xf bank_mask:0xf bound_ctrl:1
	s_nop 1
	v_add_f32_dpp v81, v81, v81 row_mirror row_mask:0xf bank_mask:0xf bound_ctrl:1
	v_mov_b32_e32 v110, v81
	s_nop 1
	v_permlane16_swap_b32_e32 v81, v110
	v_add_f32_e32 v81, v81, v110
	v_mov_b32_e32 v110, v81
	s_nop 1
	v_permlane32_swap_b32_e32 v81, v110
	v_add_f32_e32 v81, v81, v110
	v_fmamk_f32 v81, v81, 0x3c000000, v236
	v_mul_f32_e32 v110, 0x4b800000, v81
	v_cmp_gt_f32_e32 vcc, s7, v81
	s_nop 1
	v_cndmask_b32_e32 v81, v81, v110, vcc
	v_rsq_f32_e32 v81, v81
	s_nop 0
	v_mul_f32_e32 v110, 0x45800000, v81
	v_cndmask_b32_e32 v81, v81, v110, vcc
	v_mul_f32_e32 v81, v235, v81
	v_mul_f32_e32 v79, v79, v81
	v_mul_f32_e32 v78, v78, v81
	v_mul_f32_e32 v79, v3, v79
	v_mul_f32_e32 v78, v2, v78
	v_mul_f32_e32 v106, v79, v106
	v_mul_f32_e32 v78, v78, v80
	v_cvt_pk_bf16_f32 v106, v78, v106
	global_store_dword v[140:141], v106, off
	s_waitcnt vmcnt(19)
; __device__ __forceinline__ void phase_attn(const Params& p, int l, unsigned char* smem) {
;     ...
;             for (int i = 0; i < 32; ++i) {
;                 const int qrow = w * 32 + i;
;                 const float2 a0 = *(const float2*)(blk + (size_t)qrow * 128 + lane * 2);
;                 const float2 a1 = *(const float2*)(blk + (size_t)(256 + qrow) * 128 + lane * 2);
;                 const unsigned zz = *(const unsigned*)(p.sz + (grow0 + qrow) * D + hh * 128 + lane * 2);
;                 const float o0 = a0.x - lam * a1.x, o1 = a0.y - lam * a1.y;
;                 float ss = o0 * o0 + o1 * o1;
;                 ss = wave_sum64(ss);
;                 const float rstd = rsqrtf(ss * (1.0f / 128.0f) + EPS) * post;
;                 const float z0 = __uint_as_float(zz << 16), z1 = __uint_as_float(zz & 0xffff0000u);
;                 *(unsigned*)(p.og + (grow0 + qrow) * D + hh * 128 + lane * 2) = pk_bf16(o0 * rstd * g0 * z0, o1 * rstd * g1 * z1);
;             }
	v_fma_f32 v83, -v17, v85, v83
	v_fma_f32 v82, -v17, v84, v82
	v_mul_f32_e32 v85, v83, v83
	v_fmac_f32_e32 v85, v82, v82
	v_lshlrev_b32_e32 v84, 16, v107
	v_and_b32_e32 v107, 0xffff0000, v107
	v_add_f32_dpp v85, v85, v85 quad_perm:[1,0,3,2] row_mask:0xf bank_mask:0xf bound_ctrl:1
	s_nop 1
	v_add_f32_dpp v85, v85, v85 quad_perm:[2,3,0,1] row_mask:0xf bank_mask:0xf bound_ctrl:1
	s_nop 1
	v_add_f32_dpp v85, v85, v85 row_half_mirror row_mask:0xf bank_mask:0xf bound_ctrl:1
	s_nop 1
	v_add_f32_dpp v85, v85, v85 row_mirror row_mask:0xf bank_mask:0xf bound_ctrl:1
	v_mov_b32_e32 v110, v85
	s_nop 1
	v_permlane16_swap_b32_e32 v85, v110
	v_add_f32_e32 v85, v85, v110
	v_mov_b32_e32 v110, v85
	s_nop 1
	v_permlane32_swap_b32_e32 v85, v110
	v_add_f32_e32 v85, v85, v110
	v_fmamk_f32 v85, v85, 0x3c000000, v236
	v_mul_f32_e32 v110, 0x4b800000, v85
	v_cmp_gt_f32_e32 vcc, s7, v85
	s_nop 1
	v_cndmask_b32_e32 v85, v85, v110, vcc
	v_rsq_f32_e32 v85, v85
	s_nop 0
	v_mul_f32_e32 v110, 0x45800000, v85
	v_cndmask_b32_e32 v85, v85, v110, vcc
	v_mul_f32_e32 v85, v235, v85
	v_mul_f32_e32 v83, v83, v85
	v_mul_f32_e32 v82, v82, v85
	v_mul_f32_e32 v83, v3, v83
	v_mul_f32_e32 v82, v2, v82
	v_mul_f32_e32 v107, v83, v107
	v_mul_f32_e32 v82, v82, v84
	v_cvt_pk_bf16_f32 v107, v82, v107
	global_store_dword v[140:141], v107, off offset:2048
	s_waitcnt vmcnt(17)
	v_fma_f32 v87, -v17, v89, v87
	v_fma_f32 v86, -v17, v88, v86
	v_mul_f32_e32 v89, v87, v87
	v_fmac_f32_e32 v89, v86, v86
	v_lshlrev_b32_e32 v88, 16, v108
	v_and_b32_e32 v108, 0xffff0000, v108
	v_add_f32_dpp v89, v89, v89 quad_perm:[1,0,3,2] row_mask:0xf bank_mask:0xf bound_ctrl:1
	s_nop 1
	v_add_f32_dpp v89, v89, v89 quad_perm:[2,3,0,1] row_mask:0xf bank_mask:0xf bound_ctrl:1
	s_nop 1
	v_add_f32_dpp v89, v89, v89 row_half_mirror row_mask:0xf bank_mask:0xf bound_ctrl:1
	s_nop 1
	v_add_f32_dpp v89, v89, v89 row_mirror row_mask:0xf bank_mask:0xf bound_ctrl:1
	v_mov_b32_e32 v110, v89
	s_nop 1
	v_permlane16_swap_b32_e32 v89, v110
	v_add_f32_e32 v89, v89, v110
	v_mov_b32_e32 v110, v89
	s_nop 1
	v_permlane32_swap_b32_e32 v89, v110
	v_add_f32_e32 v89, v89, v110
	v_fmamk_f32 v89, v89, 0x3c000000, v236
	v_mul_f32_e32 v110, 0x4b800000, v89
	v_cmp_gt_f32_e32 vcc, s7, v89
	s_nop 1
	v_cndmask_b32_e32 v89, v89, v110, vcc
	v_rsq_f32_e32 v89, v89
	s_nop 0
	v_mul_f32_e32 v110, 0x45800000, v89
	v_cndmask_b32_e32 v89, v89, v110, vcc
	v_mul_f32_e32 v89, v235, v89
	v_mul_f32_e32 v87, v87, v89
	v_mul_f32_e32 v86, v86, v89
	v_mul_f32_e32 v87, v3, v87
	v_mul_f32_e32 v86, v2, v86
	v_mul_f32_e32 v108, v87, v108
	v_mul_f32_e32 v86, v86, v88
	v_cvt_pk_bf16_f32 v108, v86, v108
	global_store_dword v[142:143], v108, off
	s_waitcnt vmcnt(15)
	v_fma_f32 v91, -v17, v93, v91
	v_fma_f32 v90, -v17, v92, v90
	v_mul_f32_e32 v93, v91, v91
	v_fmac_f32_e32 v93, v90, v90
	v_lshlrev_b32_e32 v92, 16, v109
	v_and_b32_e32 v109, 0xffff0000, v109
	v_add_f32_dpp v93, v93, v93 quad_perm:[1,0,3,2] row_mask:0xf bank_mask:0xf bound_ctrl:1
	s_nop 1
	v_add_f32_dpp v93, v93, v93 quad_perm:[2,3,0,1] row_mask:0xf bank_mask:0xf bound_ctrl:1
	s_nop 1
	v_add_f32_dpp v93, v93, v93 row_half_mirror row_mask:0xf bank_mask:0xf bound_ctrl:1
	s_nop 1
	v_add_f32_dpp v93, v93, v93 row_mirror row_mask:0xf bank_mask:0xf bound_ctrl:1
	v_mov_b32_e32 v110, v93
	s_nop 1
	v_permlane16_swap_b32_e32 v93, v110
	v_add_f32_e32 v93, v93, v110
	v_mov_b32_e32 v110, v93
	s_nop 1
	v_permlane32_swap_b32_e32 v93, v110
	v_add_f32_e32 v93, v93, v110
	v_fmamk_f32 v93, v93, 0x3c000000, v236
	v_mul_f32_e32 v110, 0x4b800000, v93
	v_cmp_gt_f32_e32 vcc, s7, v93
	s_nop 1
	v_cndmask_b32_e32 v93, v93, v110, vcc
	v_rsq_f32_e32 v93, v93
	s_nop 0
	v_mul_f32_e32 v110, 0x45800000, v93
	v_cndmask_b32_e32 v93, v93, v110, vcc
	v_mul_f32_e32 v93, v235, v93
	v_mul_f32_e32 v91, v91, v93
	v_mul_f32_e32 v90, v90, v93
	v_mul_f32_e32 v91, v3, v91
	v_mul_f32_e32 v90, v2, v90
	v_mul_f32_e32 v109, v91, v109
	v_mul_f32_e32 v90, v90, v92
	v_cvt_pk_bf16_f32 v109, v90, v109
	global_store_dword v[142:143], v109, off offset:2048
	s_cmpk_eq_i32 s4, 0x4000
	s_cbranch_scc0 .Ldv2fin_loop
	v_readlane_b32 s4, v254, 4
	s_add_i32 s35, s35, s4
	s_movk_i32 s89, 0x3000
	s_movk_i32 s60, 0x1000
	s_cmp_ge_u32 s35, s34
	s_barrier
	s_cbranch_scc0 .LBB0_256
